# XCD-local barriers: L1 invalidate issued right behind the arrive atomic (overlaps the wait for the other workgroups), counted vmcnt instead of drain
# speedup vs baseline: 1.0090x; 1.0090x over previous
.LBB0_449:
	s_add_u32 s0, s86, 0x14000
	v_writelane_b32 v233, s0, 22
	s_addc_u32 s0, s87, 0
	v_writelane_b32 v233, s0, 23
	s_add_i32 s0, 0, 0x20168
	s_waitcnt vmcnt(0)
	v_mov_b32_e32 v0, s0
	ds_read_b32 v0, v0
	s_waitcnt lgkmcnt(0)
	v_cmp_eq_u32_e32 vcc, 0, v0
	s_cbranch_vccnz .LBB0_463
	v_mov_b32_e32 v0, 0
	s_waitcnt vmcnt(0)
	v_readlane_b32 s0, v233, 13
	v_mbcnt_lo_u32_b32 v0, -1, v0
	v_mbcnt_hi_u32_b32 v0, -1, v0
	v_cmp_eq_u32_e32 vcc, s0, v0
	s_barrier
	s_and_saveexec_b64 s[0:1], vcc
	s_cbranch_execz .LBB0_469
	s_add_i32 s2, 0, 0x20160
	v_mov_b32_e32 v0, s2
	s_waitcnt vmcnt(0) expcnt(0) lgkmcnt(0)
	ds_read_b32 v0, v0
	s_mov_b64 s[4:5], exec
	v_readlane_b32 s2, v233, 4
	s_lshl_b32 s2, s2, 8
	v_readlane_b32 s3, v233, 22
	v_mbcnt_lo_u32_b32 v1, s4, 0
	s_add_u32 s2, s3, s2
	v_readlane_b32 s3, v233, 23
	v_mbcnt_hi_u32_b32 v1, s5, v1
	s_addc_u32 s3, s3, 0
	v_cmp_eq_u32_e32 vcc, 0, v1
	s_and_saveexec_b64 s[6:7], vcc
	s_cbranch_execz .LBB0_453
	s_bcnt1_i32_b64 s4, s[4:5]
	v_mov_b32_e32 v2, 0
	v_mov_b32_e32 v3, s4
	global_atomic_add v2, v2, v3, s[2:3] sc0
	buffer_inv sc1
.LBB0_453:
	s_or_b64 exec, exec, s[6:7]
	s_waitcnt lgkmcnt(0)
	v_cvt_f32_u32_e32 v3, v0
	s_waitcnt vmcnt(1)
	v_readfirstlane_b32 s4, v2
	s_mov_b64 s[6:7], -1
	v_rcp_iflag_f32_e32 v3, v3
	v_add_u32_e32 v1, s4, v1
	v_add_u32_e32 v4, 1, v1
	s_add_u32 s4, s2, 0x1000
	v_mul_f32_e32 v2, 0x4f7ffffe, v3
	v_cvt_u32_f32_e32 v2, v2
	v_sub_u32_e32 v3, 0, v0
	s_addc_u32 s5, s3, 0
	v_mul_lo_u32 v3, v3, v2
	v_mul_hi_u32 v3, v2, v3
	v_add_u32_e32 v2, v2, v3
	v_mul_hi_u32 v2, v1, v2
	v_mul_lo_u32 v3, v2, v0
	v_sub_u32_e32 v1, v1, v3
	v_add_u32_e32 v5, 1, v2
	v_cmp_ge_u32_e32 vcc, v1, v0
	v_sub_u32_e32 v3, v1, v0
	s_nop 0
	v_cndmask_b32_e32 v2, v2, v5, vcc
	v_cndmask_b32_e32 v1, v1, v3, vcc
	v_add_u32_e32 v3, 1, v2
	v_cmp_ge_u32_e32 vcc, v1, v0
	s_nop 1
	v_cndmask_b32_e32 v2, v2, v3, vcc
	v_mul_lo_u32 v1, v0, v2
	v_add_u32_e32 v0, v1, v0
	v_cmp_ne_u32_e32 vcc, v4, v0
	v_mov_b64_e32 v[0:1], s[4:5]
	s_and_saveexec_b64 s[2:3], vcc
	s_cbranch_execz .LBB0_466
	v_mov_b32_e32 v0, 0
	global_load_dword v1, v0, s[4:5] sc1
	s_mov_b64 s[10:11], 0
	s_waitcnt vmcnt(0)
	v_cmp_eq_u32_e32 vcc, v1, v2
	s_and_saveexec_b64 s[8:9], vcc
	s_cbranch_execz .LBB0_465
	s_add_u32 s6, s86, 0x4200
	s_addc_u32 s7, s87, 0
	s_mov_b32 s20, 1
	s_branch .LBB0_457

.LBB0_468:
	s_or_b64 exec, exec, s[2:3]
	s_waitcnt vmcnt(1)

.LBB0_572:
	s_add_i32 s0, 0, 0x20168
	v_mov_b32_e32 v0, s0
	ds_read_b32 v0, v0
	s_waitcnt lgkmcnt(0)
	v_cmp_eq_u32_e32 vcc, 0, v0
	s_cbranch_vccnz .LBB0_586
	v_mov_b32_e32 v0, 0
	s_waitcnt vmcnt(0)
	v_readlane_b32 s0, v233, 13
	v_mbcnt_lo_u32_b32 v0, -1, v0
	v_mbcnt_hi_u32_b32 v0, -1, v0
	v_cmp_eq_u32_e32 vcc, s0, v0
	s_waitcnt vmcnt(0)
	s_barrier
	s_and_saveexec_b64 s[0:1], vcc
	s_cbranch_execz .LBB0_592
	s_add_i32 s4, 0, 0x20160
	v_mov_b32_e32 v0, s4
	s_waitcnt vmcnt(0) expcnt(0) lgkmcnt(0)
	ds_read_b32 v0, v0
	s_mov_b64 s[6:7], exec
	v_readlane_b32 s4, v233, 4
	s_lshl_b32 s4, s4, 8
	v_readlane_b32 s5, v233, 22
	v_mbcnt_lo_u32_b32 v1, s6, 0
	s_add_u32 s4, s5, s4
	v_readlane_b32 s5, v233, 23
	v_mbcnt_hi_u32_b32 v1, s7, v1
	s_addc_u32 s5, s5, 0
	v_cmp_eq_u32_e32 vcc, 0, v1
	s_and_saveexec_b64 s[8:9], vcc
	s_cbranch_execz .LBB0_576
	s_bcnt1_i32_b64 s6, s[6:7]
	v_mov_b32_e32 v2, 0
	v_mov_b32_e32 v3, s6
	global_atomic_add v2, v2, v3, s[4:5] sc0
	buffer_inv sc1
.LBB0_576:
	s_or_b64 exec, exec, s[8:9]
	s_waitcnt lgkmcnt(0)
	v_cvt_f32_u32_e32 v3, v0
	s_waitcnt vmcnt(1)
	v_readfirstlane_b32 s6, v2
	s_mov_b64 s[8:9], -1
	v_rcp_iflag_f32_e32 v3, v3
	v_add_u32_e32 v1, s6, v1
	v_add_u32_e32 v4, 1, v1
	s_add_u32 s6, s4, 0x1000
	v_mul_f32_e32 v2, 0x4f7ffffe, v3
	v_cvt_u32_f32_e32 v2, v2
	v_sub_u32_e32 v3, 0, v0
	s_addc_u32 s7, s5, 0
	v_mul_lo_u32 v3, v3, v2
	v_mul_hi_u32 v3, v2, v3
	v_add_u32_e32 v2, v2, v3
	v_mul_hi_u32 v2, v1, v2
	v_mul_lo_u32 v3, v2, v0
	v_sub_u32_e32 v1, v1, v3
	v_add_u32_e32 v5, 1, v2
	v_cmp_ge_u32_e32 vcc, v1, v0
	v_sub_u32_e32 v3, v1, v0
	s_nop 0
	v_cndmask_b32_e32 v2, v2, v5, vcc
	v_cndmask_b32_e32 v1, v1, v3, vcc
	v_add_u32_e32 v3, 1, v2
	v_cmp_ge_u32_e32 vcc, v1, v0
	s_nop 1
	v_cndmask_b32_e32 v2, v2, v3, vcc
	v_mul_lo_u32 v1, v0, v2
	v_add_u32_e32 v0, v1, v0
	v_cmp_ne_u32_e32 vcc, v4, v0
	v_mov_b64_e32 v[0:1], s[6:7]
	s_and_saveexec_b64 s[4:5], vcc
	s_cbranch_execz .LBB0_589
	v_mov_b32_e32 v0, 0
	global_load_dword v1, v0, s[6:7] sc1
	s_mov_b64 s[12:13], 0
	s_waitcnt vmcnt(0)
	v_cmp_eq_u32_e32 vcc, v1, v2
	s_and_saveexec_b64 s[10:11], vcc
	s_cbranch_execz .LBB0_588
	s_add_u32 s8, s86, 0x4200
	s_addc_u32 s9, s87, 0
	s_mov_b32 s22, 1
	s_branch .LBB0_580

.LBB0_591:
	s_or_b64 exec, exec, s[4:5]
	s_waitcnt vmcnt(1)

.LBB0_1351:
	s_add_i32 s0, 0, 0x20168
	v_mov_b32_e32 v0, s0
	ds_read_b32 v0, v0
	s_waitcnt lgkmcnt(0)
	v_cmp_eq_u32_e32 vcc, 0, v0
	s_cbranch_vccnz .LBB0_1365
	v_mov_b32_e32 v0, 0
	s_waitcnt vmcnt(0)
	v_readlane_b32 s0, v233, 13
	v_mbcnt_lo_u32_b32 v0, -1, v0
	v_mbcnt_hi_u32_b32 v0, -1, v0
	v_cmp_eq_u32_e32 vcc, s0, v0
	s_barrier
	s_and_saveexec_b64 s[0:1], vcc
	s_cbranch_execz .LBB0_1371
	s_add_i32 s4, 0, 0x20160
	v_mov_b32_e32 v0, s4
	s_waitcnt vmcnt(0) expcnt(0) lgkmcnt(0)
	ds_read_b32 v0, v0
	s_mov_b64 s[6:7], exec
	v_readlane_b32 s4, v233, 4
	s_lshl_b32 s4, s4, 8
	v_readlane_b32 s5, v233, 22
	v_mbcnt_lo_u32_b32 v1, s6, 0
	s_add_u32 s4, s5, s4
	v_readlane_b32 s5, v233, 23
	v_mbcnt_hi_u32_b32 v1, s7, v1
	s_addc_u32 s5, s5, 0
	v_cmp_eq_u32_e32 vcc, 0, v1
	s_and_saveexec_b64 s[8:9], vcc
	s_cbranch_execz .LBB0_1355
	s_bcnt1_i32_b64 s6, s[6:7]
	v_mov_b32_e32 v2, 0
	v_mov_b32_e32 v3, s6
	global_atomic_add v2, v2, v3, s[4:5] sc0
	buffer_inv sc1
.LBB0_1355:
	s_or_b64 exec, exec, s[8:9]
	s_waitcnt lgkmcnt(0)
	v_cvt_f32_u32_e32 v3, v0
	s_waitcnt vmcnt(1)
	v_readfirstlane_b32 s6, v2
	s_mov_b64 s[8:9], -1
	v_rcp_iflag_f32_e32 v3, v3
	v_add_u32_e32 v1, s6, v1
	v_add_u32_e32 v4, 1, v1
	s_add_u32 s6, s4, 0x1000
	v_mul_f32_e32 v2, 0x4f7ffffe, v3
	v_cvt_u32_f32_e32 v2, v2
	v_sub_u32_e32 v3, 0, v0
	s_addc_u32 s7, s5, 0
	v_mul_lo_u32 v3, v3, v2
	v_mul_hi_u32 v3, v2, v3
	v_add_u32_e32 v2, v2, v3
	v_mul_hi_u32 v2, v1, v2
	v_mul_lo_u32 v3, v2, v0
	v_sub_u32_e32 v1, v1, v3
	v_add_u32_e32 v5, 1, v2
	v_cmp_ge_u32_e32 vcc, v1, v0
	v_sub_u32_e32 v3, v1, v0
	s_nop 0
	v_cndmask_b32_e32 v2, v2, v5, vcc
	v_cndmask_b32_e32 v1, v1, v3, vcc
	v_add_u32_e32 v3, 1, v2
	v_cmp_ge_u32_e32 vcc, v1, v0
	s_nop 1
	v_cndmask_b32_e32 v2, v2, v3, vcc
	v_mul_lo_u32 v1, v0, v2
	v_add_u32_e32 v0, v1, v0
	v_cmp_ne_u32_e32 vcc, v4, v0
	v_mov_b64_e32 v[0:1], s[6:7]
	s_and_saveexec_b64 s[4:5], vcc
	s_cbranch_execz .LBB0_1368
	v_mov_b32_e32 v0, 0
	global_load_dword v1, v0, s[6:7] sc1
	s_mov_b64 s[12:13], 0
	s_waitcnt vmcnt(0)
	v_cmp_eq_u32_e32 vcc, v1, v2
	s_and_saveexec_b64 s[10:11], vcc
	s_cbranch_execz .LBB0_1367
	s_add_u32 s8, s70, 0x4200
	s_addc_u32 s9, s71, 0
	s_mov_b32 s22, 1
	s_branch .LBB0_1359

.LBB0_1493:
	s_add_i32 s0, 0, 0x20168
	v_mov_b32_e32 v0, s0
	ds_read_b32 v0, v0
	s_waitcnt lgkmcnt(0)
	v_cmp_eq_u32_e32 vcc, 0, v0
	s_cbranch_vccnz .LBB0_1507
	v_mov_b32_e32 v0, 0
	s_waitcnt vmcnt(0)
	v_readlane_b32 s0, v233, 13
	v_mbcnt_lo_u32_b32 v0, -1, v0
	v_mbcnt_hi_u32_b32 v0, -1, v0
	v_cmp_eq_u32_e32 vcc, s0, v0
	s_barrier
	s_and_saveexec_b64 s[0:1], vcc
	s_cbranch_execz .LBB0_1513
	s_add_i32 s6, 0, 0x20160
	v_mov_b32_e32 v0, s6
	s_waitcnt vmcnt(0) expcnt(0) lgkmcnt(0)
	ds_read_b32 v0, v0
	s_mov_b64 s[8:9], exec
	v_readlane_b32 s6, v233, 4
	s_lshl_b32 s6, s6, 8
	v_readlane_b32 s7, v233, 22
	v_mbcnt_lo_u32_b32 v1, s8, 0
	s_add_u32 s6, s7, s6
	v_readlane_b32 s7, v233, 23
	v_mbcnt_hi_u32_b32 v1, s9, v1
	s_addc_u32 s7, s7, 0
	v_cmp_eq_u32_e32 vcc, 0, v1
	s_and_saveexec_b64 s[10:11], vcc
	s_cbranch_execz .LBB0_1497
	s_bcnt1_i32_b64 s8, s[8:9]
	v_mov_b32_e32 v2, 0
	v_mov_b32_e32 v3, s8
	global_atomic_add v2, v2, v3, s[6:7] sc0
	buffer_inv sc1
.LBB0_1497:
	s_or_b64 exec, exec, s[10:11]
	s_waitcnt lgkmcnt(0)
	v_cvt_f32_u32_e32 v3, v0
	s_waitcnt vmcnt(1)
	v_readfirstlane_b32 s8, v2
	s_mov_b64 s[10:11], -1
	v_rcp_iflag_f32_e32 v3, v3
	v_add_u32_e32 v1, s8, v1
	v_add_u32_e32 v4, 1, v1
	s_add_u32 s8, s6, 0x1000
	v_mul_f32_e32 v2, 0x4f7ffffe, v3
	v_cvt_u32_f32_e32 v2, v2
	v_sub_u32_e32 v3, 0, v0
	s_addc_u32 s9, s7, 0
	v_mul_lo_u32 v3, v3, v2
	v_mul_hi_u32 v3, v2, v3
	v_add_u32_e32 v2, v2, v3
	v_mul_hi_u32 v2, v1, v2
	v_mul_lo_u32 v3, v2, v0
	v_sub_u32_e32 v1, v1, v3
	v_add_u32_e32 v5, 1, v2
	v_cmp_ge_u32_e32 vcc, v1, v0
	v_sub_u32_e32 v3, v1, v0
	s_nop 0
	v_cndmask_b32_e32 v2, v2, v5, vcc
	v_cndmask_b32_e32 v1, v1, v3, vcc
	v_add_u32_e32 v3, 1, v2
	v_cmp_ge_u32_e32 vcc, v1, v0
	s_nop 1
	v_cndmask_b32_e32 v2, v2, v3, vcc
	v_mul_lo_u32 v1, v0, v2
	v_add_u32_e32 v0, v1, v0
	v_cmp_ne_u32_e32 vcc, v4, v0
	v_mov_b64_e32 v[0:1], s[8:9]
	s_and_saveexec_b64 s[6:7], vcc
	s_cbranch_execz .LBB0_1510
	v_mov_b32_e32 v0, 0
	global_load_dword v1, v0, s[8:9] sc1
	s_mov_b64 s[14:15], 0
	s_waitcnt vmcnt(0)
	v_cmp_eq_u32_e32 vcc, v1, v2
	s_and_saveexec_b64 s[12:13], vcc
	s_cbranch_execz .LBB0_1509
	s_add_u32 s10, s70, 0x4200
	s_addc_u32 s11, s71, 0
	s_mov_b32 s24, 1
	s_branch .LBB0_1501

.LBB0_1512:
	s_or_b64 exec, exec, s[6:7]
	s_waitcnt vmcnt(1)

.LBB0_1620:
	s_add_i32 s0, 0, 0x20168
	v_mov_b32_e32 v0, s0
	ds_read_b32 v0, v0
	s_waitcnt lgkmcnt(0)
	v_cmp_eq_u32_e32 vcc, 0, v0
	s_cbranch_vccnz .LBB0_1634
	v_mov_b32_e32 v0, 0
	s_waitcnt vmcnt(0)
	v_readlane_b32 s0, v233, 13
	v_mbcnt_lo_u32_b32 v0, -1, v0
	v_mbcnt_hi_u32_b32 v0, -1, v0
	v_cmp_eq_u32_e32 vcc, s0, v0
	s_barrier
	s_and_saveexec_b64 s[0:1], vcc
	v_readlane_b32 s51, v233, 30
	s_cbranch_execz .LBB0_1640
	s_add_i32 s2, 0, 0x20160
	v_mov_b32_e32 v0, s2
	s_waitcnt vmcnt(0) expcnt(0) lgkmcnt(0)
	ds_read_b32 v0, v0
	s_mov_b64 s[6:7], exec
	v_readlane_b32 s2, v233, 4
	s_lshl_b32 s2, s2, 8
	v_readlane_b32 s3, v233, 22
	v_mbcnt_lo_u32_b32 v1, s6, 0
	s_add_u32 s2, s3, s2
	v_readlane_b32 s3, v233, 23
	v_mbcnt_hi_u32_b32 v1, s7, v1
	s_addc_u32 s3, s3, 0
	v_cmp_eq_u32_e32 vcc, 0, v1
	s_and_saveexec_b64 s[8:9], vcc
	s_cbranch_execz .LBB0_1624
	s_bcnt1_i32_b64 s6, s[6:7]
	v_mov_b32_e32 v2, 0
	v_mov_b32_e32 v3, s6
	global_atomic_add v2, v2, v3, s[2:3] sc0
	buffer_inv sc1
.LBB0_1624:
	s_or_b64 exec, exec, s[8:9]
	s_waitcnt lgkmcnt(0)
	v_cvt_f32_u32_e32 v3, v0
	s_waitcnt vmcnt(1)
	v_readfirstlane_b32 s6, v2
	s_mov_b64 s[8:9], -1
	v_rcp_iflag_f32_e32 v3, v3
	v_add_u32_e32 v1, s6, v1
	v_add_u32_e32 v4, 1, v1
	s_add_u32 s6, s2, 0x1000
	v_mul_f32_e32 v2, 0x4f7ffffe, v3
	v_cvt_u32_f32_e32 v2, v2
	v_sub_u32_e32 v3, 0, v0
	s_addc_u32 s7, s3, 0
	v_mul_lo_u32 v3, v3, v2
	v_mul_hi_u32 v3, v2, v3
	v_add_u32_e32 v2, v2, v3
	v_mul_hi_u32 v2, v1, v2
	v_mul_lo_u32 v3, v2, v0
	v_sub_u32_e32 v1, v1, v3
	v_add_u32_e32 v5, 1, v2
	v_cmp_ge_u32_e32 vcc, v1, v0
	v_sub_u32_e32 v3, v1, v0
	s_nop 0
	v_cndmask_b32_e32 v2, v2, v5, vcc
	v_cndmask_b32_e32 v1, v1, v3, vcc
	v_add_u32_e32 v3, 1, v2
	v_cmp_ge_u32_e32 vcc, v1, v0
	s_nop 1
	v_cndmask_b32_e32 v2, v2, v3, vcc
	v_mul_lo_u32 v1, v0, v2
	v_add_u32_e32 v0, v1, v0
	v_cmp_ne_u32_e32 vcc, v4, v0
	v_mov_b64_e32 v[0:1], s[6:7]
	s_and_saveexec_b64 s[2:3], vcc
	s_cbranch_execz .LBB0_1637
	v_mov_b32_e32 v0, 0
	global_load_dword v1, v0, s[6:7] sc1
	s_mov_b64 s[14:15], 0
	s_waitcnt vmcnt(0)
	v_cmp_eq_u32_e32 vcc, v1, v2
	s_and_saveexec_b64 s[12:13], vcc
	s_cbranch_execz .LBB0_1636
	s_add_u32 s8, s70, 0x4200
	s_addc_u32 s9, s71, 0
	s_mov_b32 s26, 1
	s_branch .LBB0_1628

.LBB0_1759:
	s_add_i32 s0, 0, 0x20168
	v_mov_b32_e32 v0, s0
	ds_read_b32 v0, v0
	s_waitcnt lgkmcnt(0)
	v_cmp_eq_u32_e32 vcc, 0, v0
	s_cbranch_vccnz .LBB0_1773
	v_mov_b32_e32 v0, 0
	s_waitcnt vmcnt(0)
	v_readlane_b32 s0, v233, 13
	v_mbcnt_lo_u32_b32 v0, -1, v0
	v_mbcnt_hi_u32_b32 v0, -1, v0
	v_cmp_eq_u32_e32 vcc, s0, v0
	s_waitcnt vmcnt(0)
	s_barrier
	s_and_saveexec_b64 s[0:1], vcc
	s_cbranch_execz .LBB0_1779
	s_add_i32 s6, 0, 0x20160
	v_mov_b32_e32 v0, s6
	s_waitcnt vmcnt(0) expcnt(0) lgkmcnt(0)
	ds_read_b32 v0, v0
	s_mov_b64 s[8:9], exec
	v_readlane_b32 s6, v233, 4
	s_lshl_b32 s6, s6, 8
	v_readlane_b32 s7, v233, 22
	v_mbcnt_lo_u32_b32 v1, s8, 0
	s_add_u32 s6, s7, s6
	v_readlane_b32 s7, v233, 23
	v_mbcnt_hi_u32_b32 v1, s9, v1
	s_addc_u32 s7, s7, 0
	v_cmp_eq_u32_e32 vcc, 0, v1
	s_and_saveexec_b64 s[10:11], vcc
	s_cbranch_execz .LBB0_1763
	s_bcnt1_i32_b64 s8, s[8:9]
	v_mov_b32_e32 v2, 0
	v_mov_b32_e32 v3, s8
	global_atomic_add v2, v2, v3, s[6:7] sc0
	buffer_inv sc1
.LBB0_1763:
	s_or_b64 exec, exec, s[10:11]
	s_waitcnt lgkmcnt(0)
	v_cvt_f32_u32_e32 v3, v0
	s_waitcnt vmcnt(1)
	v_readfirstlane_b32 s8, v2
	s_mov_b64 s[10:11], -1
	v_rcp_iflag_f32_e32 v3, v3
	v_add_u32_e32 v1, s8, v1
	v_add_u32_e32 v4, 1, v1
	s_add_u32 s8, s6, 0x1000
	v_mul_f32_e32 v2, 0x4f7ffffe, v3
	v_cvt_u32_f32_e32 v2, v2
	v_sub_u32_e32 v3, 0, v0
	s_addc_u32 s9, s7, 0
	v_mul_lo_u32 v3, v3, v2
	v_mul_hi_u32 v3, v2, v3
	v_add_u32_e32 v2, v2, v3
	v_mul_hi_u32 v2, v1, v2
	v_mul_lo_u32 v3, v2, v0
	v_sub_u32_e32 v1, v1, v3
	v_add_u32_e32 v5, 1, v2
	v_cmp_ge_u32_e32 vcc, v1, v0
	v_sub_u32_e32 v3, v1, v0
	s_nop 0
	v_cndmask_b32_e32 v2, v2, v5, vcc
	v_cndmask_b32_e32 v1, v1, v3, vcc
	v_add_u32_e32 v3, 1, v2
	v_cmp_ge_u32_e32 vcc, v1, v0
	s_nop 1
	v_cndmask_b32_e32 v2, v2, v3, vcc
	v_mul_lo_u32 v1, v0, v2
	v_add_u32_e32 v0, v1, v0
	v_cmp_ne_u32_e32 vcc, v4, v0
	v_mov_b64_e32 v[0:1], s[8:9]
	s_and_saveexec_b64 s[6:7], vcc
	s_cbranch_execz .LBB0_1776
	v_mov_b32_e32 v0, 0
	global_load_dword v1, v0, s[8:9] sc1
	s_mov_b64 s[14:15], 0
	s_waitcnt vmcnt(0)
	v_cmp_eq_u32_e32 vcc, v1, v2
	s_and_saveexec_b64 s[12:13], vcc
	s_cbranch_execz .LBB0_1775
	s_add_u32 s10, s70, 0x4200
	s_addc_u32 s11, s71, 0
	s_mov_b32 s26, 1
	s_branch .LBB0_1767

.LBB0_1890:
	s_or_b64 exec, exec, s[10:11]
	s_waitcnt lgkmcnt(0)
	v_cvt_f32_u32_e32 v3, v0
	s_waitcnt vmcnt(1)
	v_readfirstlane_b32 s8, v2
	s_mov_b64 s[10:11], -1
	v_rcp_iflag_f32_e32 v3, v3
	v_add_u32_e32 v1, s8, v1
	v_add_u32_e32 v4, 1, v1
	s_add_u32 s8, s6, 0x1000
	v_mul_f32_e32 v2, 0x4f7ffffe, v3
	v_cvt_u32_f32_e32 v2, v2
	v_sub_u32_e32 v3, 0, v0
	s_addc_u32 s9, s7, 0
	v_mul_lo_u32 v3, v3, v2
	v_mul_hi_u32 v3, v2, v3
	v_add_u32_e32 v2, v2, v3
	v_mul_hi_u32 v2, v1, v2
	v_mul_lo_u32 v3, v2, v0
	v_sub_u32_e32 v1, v1, v3
	v_add_u32_e32 v5, 1, v2
	v_cmp_ge_u32_e32 vcc, v1, v0
	v_sub_u32_e32 v3, v1, v0
	s_nop 0
	v_cndmask_b32_e32 v2, v2, v5, vcc
	v_cndmask_b32_e32 v1, v1, v3, vcc
	v_add_u32_e32 v3, 1, v2
	v_cmp_ge_u32_e32 vcc, v1, v0
	s_nop 1
	v_cndmask_b32_e32 v2, v2, v3, vcc
	v_mul_lo_u32 v1, v0, v2
	v_add_u32_e32 v0, v1, v0
	v_cmp_ne_u32_e32 vcc, v4, v0
	v_mov_b64_e32 v[0:1], s[8:9]
	s_and_saveexec_b64 s[6:7], vcc
	s_cbranch_execz .LBB0_1903
	v_mov_b32_e32 v0, 0
	global_load_dword v1, v0, s[8:9] sc1
	s_mov_b64 s[18:19], 0
	s_waitcnt vmcnt(0)
	v_cmp_eq_u32_e32 vcc, v1, v2
	s_and_saveexec_b64 s[14:15], vcc
	s_cbranch_execz .LBB0_1902
	s_add_u32 s10, s70, 0x4200
	s_addc_u32 s11, s71, 0
	s_mov_b32 s28, 1
	s_branch .LBB0_1894

.LBB0_2053:
	s_or_b64 exec, exec, s[10:11]
	s_waitcnt lgkmcnt(0)
	v_cvt_f32_u32_e32 v3, v0
	s_waitcnt vmcnt(1)
	v_readfirstlane_b32 s8, v2
	s_mov_b64 s[10:11], -1
	v_rcp_iflag_f32_e32 v3, v3
	v_add_u32_e32 v1, s8, v1
	v_add_u32_e32 v4, 1, v1
	s_add_u32 s8, s6, 0x1000
	v_mul_f32_e32 v2, 0x4f7ffffe, v3
	v_cvt_u32_f32_e32 v2, v2
	v_sub_u32_e32 v3, 0, v0
	s_addc_u32 s9, s7, 0
	v_mul_lo_u32 v3, v3, v2
	v_mul_hi_u32 v3, v2, v3
	v_add_u32_e32 v2, v2, v3
	v_mul_hi_u32 v2, v1, v2
	v_mul_lo_u32 v3, v2, v0
	v_sub_u32_e32 v1, v1, v3
	v_add_u32_e32 v5, 1, v2
	v_cmp_ge_u32_e32 vcc, v1, v0
	v_sub_u32_e32 v3, v1, v0
	s_nop 0
	v_cndmask_b32_e32 v2, v2, v5, vcc
	v_cndmask_b32_e32 v1, v1, v3, vcc
	v_add_u32_e32 v3, 1, v2
	v_cmp_ge_u32_e32 vcc, v1, v0
	s_nop 1
	v_cndmask_b32_e32 v2, v2, v3, vcc
	v_mul_lo_u32 v1, v0, v2
	v_add_u32_e32 v0, v1, v0
	v_cmp_ne_u32_e32 vcc, v4, v0
	v_mov_b64_e32 v[0:1], s[8:9]
	s_and_saveexec_b64 s[6:7], vcc
	s_cbranch_execz .LBB0_2066
	v_mov_b32_e32 v0, 0
	global_load_dword v1, v0, s[8:9] sc1
	s_mov_b64 s[20:21], 0
	s_waitcnt vmcnt(0)
	v_cmp_eq_u32_e32 vcc, v1, v2
	s_and_saveexec_b64 s[18:19], vcc
	s_cbranch_execz .LBB0_2065
	s_add_u32 s10, s70, 0x4200
	s_addc_u32 s11, s71, 0
	s_mov_b32 s30, 1
	s_branch .LBB0_2057

.LBB0_2208:
	s_or_b64 exec, exec, s[2:3]
	s_add_i32 s1, 0, 0x20168
	v_mov_b32_e32 v0, s1
	ds_read_b32 v0, v0
	v_readlane_b32 s1, v233, 5
	s_lshl_b32 s1, s1, 6
	s_sub_i32 s1, 0, s1
	s_waitcnt lgkmcnt(0)
	v_cmp_ne_u32_e32 vcc, 0, v0
	s_cbranch_vccz .LBB0_2222
	v_mov_b32_e32 v0, 0
	s_waitcnt vmcnt(0)
	s_nop 0
	v_mbcnt_lo_u32_b32 v0, -1, v0
	v_mbcnt_hi_u32_b32 v0, -1, v0
	v_cmp_eq_u32_e32 vcc, s1, v0
	s_barrier
	s_and_saveexec_b64 s[2:3], vcc
	s_cbranch_execz .LBB0_2228
	s_add_i32 s4, 0, 0x20160
	v_mov_b32_e32 v0, s4
	s_waitcnt vmcnt(0) expcnt(0) lgkmcnt(0)
	ds_read_b32 v0, v0
	s_mov_b64 s[6:7], exec
	v_readlane_b32 s4, v233, 4
	s_lshl_b32 s4, s4, 8
	v_readlane_b32 s5, v233, 22
	v_mbcnt_lo_u32_b32 v1, s6, 0
	s_add_u32 s4, s5, s4
	v_readlane_b32 s5, v233, 23
	v_mbcnt_hi_u32_b32 v1, s7, v1
	s_addc_u32 s5, s5, 0
	v_cmp_eq_u32_e32 vcc, 0, v1
	s_and_saveexec_b64 s[10:11], vcc
	s_cbranch_execz .LBB0_2212
	s_bcnt1_i32_b64 s6, s[6:7]
	v_mov_b32_e32 v2, 0
	v_mov_b32_e32 v3, s6
	global_atomic_add v2, v2, v3, s[4:5] sc0
	buffer_inv sc1
.LBB0_2212:
	s_or_b64 exec, exec, s[10:11]
	s_waitcnt lgkmcnt(0)
	v_cvt_f32_u32_e32 v3, v0
	s_waitcnt vmcnt(1)
	v_readfirstlane_b32 s6, v2
	s_mov_b64 s[10:11], -1
	v_rcp_iflag_f32_e32 v3, v3
	v_add_u32_e32 v1, s6, v1
	v_add_u32_e32 v4, 1, v1
	s_add_u32 s6, s4, 0x1000
	v_mul_f32_e32 v2, 0x4f7ffffe, v3
	v_cvt_u32_f32_e32 v2, v2
	v_sub_u32_e32 v3, 0, v0
	s_addc_u32 s7, s5, 0
	v_mul_lo_u32 v3, v3, v2
	v_mul_hi_u32 v3, v2, v3
	v_add_u32_e32 v2, v2, v3
	v_mul_hi_u32 v2, v1, v2
	v_mul_lo_u32 v3, v2, v0
	v_sub_u32_e32 v1, v1, v3
	v_add_u32_e32 v5, 1, v2
	v_cmp_ge_u32_e32 vcc, v1, v0
	v_sub_u32_e32 v3, v1, v0
	s_nop 0
	v_cndmask_b32_e32 v2, v2, v5, vcc
	v_cndmask_b32_e32 v1, v1, v3, vcc
	v_add_u32_e32 v3, 1, v2
	v_cmp_ge_u32_e32 vcc, v1, v0
	s_nop 1
	v_cndmask_b32_e32 v2, v2, v3, vcc
	v_mul_lo_u32 v1, v0, v2
	v_add_u32_e32 v0, v1, v0
	v_cmp_ne_u32_e32 vcc, v4, v0
	v_mov_b64_e32 v[0:1], s[6:7]
	s_and_saveexec_b64 s[4:5], vcc
	s_cbranch_execz .LBB0_2225
	v_mov_b32_e32 v0, 0
	global_load_dword v1, v0, s[6:7] sc1
	s_mov_b64 s[16:17], 0
	s_waitcnt vmcnt(0)
	v_cmp_eq_u32_e32 vcc, v1, v2
	s_and_saveexec_b64 s[12:13], vcc
	s_cbranch_execz .LBB0_2224
	s_add_u32 s10, s70, 0x4200
	s_addc_u32 s11, s71, 0
	s_mov_b32 s26, 1
	s_branch .LBB0_2216
